# v135 + grid barrier: first WG arriving in each XCD starts an early L2 writeback (leader's final writeback unchanged)
# baseline (speedup 1.0000x reference)
; __device__ __forceinline__ unsigned xb_ld(unsigned* p)              { return __hip_atomic_load(p, __ATOMIC_RELAXED, __HIP_MEMORY_SCOPE_AGENT); }
; __device__ __forceinline__ unsigned xb_add(unsigned* p, unsigned v) { return __hip_atomic_fetch_add(p, v, __ATOMIC_RELAXED, __HIP_MEMORY_SCOPE_AGENT); }
; #define XB_SPIN(cond, bar) do { unsigned _sp = 0; while (cond) { __builtin_amdgcn_s_sleep(1); \
;     if ((++_sp & 255u) == 0u) { if (xb_ld(&(bar)[XB_TMO])) break; if (_sp > XB_SPIN_CAP) { atomicAdd(&(bar)[XB_TMO], 1u); break; } } } } while (0)
; __device__ __forceinline__ void xcd_barrier(const XcdBarrier& b, bool t0) {
;     ...
;         const unsigned old = xb_add(&bar[XB_XSUB(b.x)], 1u);
;         const unsigned gen = old / nloc;
;         if (old + 1u == (gen + 1u) * nloc) {
;             __builtin_amdgcn_fence(__ATOMIC_RELEASE, "agent");
;             asm volatile("s_waitcnt vmcnt(0)" ::: "memory");
;             const unsigned og = xb_add(&bar[XB_TOP], 1u);
;             const unsigned tg = og / nx;
;             if (og + 1u == (tg + 1u) * nx) xb_add(&bar[XB_TOPGEN], 1u);
;             else XB_SPIN(xb_ld(&bar[XB_TOPGEN]) == tg, bar);
.LBB0_917:
	s_or_b64 exec, exec, s[4:5]
	v_cvt_f32_u32_e32 v5, v3
	s_waitcnt vmcnt(0)
	v_readfirstlane_b32 s4, v4
	v_sub_u32_e32 v4, 0, v3
	v_rcp_iflag_f32_e32 v5, v5
	v_add_u32_e32 v6, s4, v0
	v_mul_f32_e32 v5, 0x4f7ffffe, v5
	v_cvt_u32_f32_e32 v5, v5
	v_mul_lo_u32 v0, v4, v5
	v_mul_hi_u32 v0, v5, v0
	v_add_u32_e32 v0, v5, v0
	v_mul_hi_u32 v0, v6, v0
	v_mul_lo_u32 v4, v0, v3
	v_sub_u32_e32 v4, v6, v4
	v_add_u32_e32 v5, 1, v0
	v_cmp_ge_u32_e32 vcc, v4, v3
	s_nop 1
	v_cndmask_b32_e32 v0, v0, v5, vcc
	v_sub_u32_e32 v5, v4, v3
	v_cndmask_b32_e32 v4, v4, v5, vcc
	v_add_u32_e32 v5, 1, v0
	v_cmp_ge_u32_e32 vcc, v4, v3
	v_add_u32_e32 v4, 1, v6
	s_nop 0
	v_cndmask_b32_e32 v0, v0, v5, vcc
	v_mul_lo_u32 v5, v3, v0
	v_cmp_eq_u32_e32 vcc, v6, v5
	s_cbranch_vccz .Lxb_nofirst
	buffer_wbl2 sc1
.Lxb_nofirst:
	v_add_u32_e32 v3, v5, v3
	v_cmp_ne_u32_e32 vcc, v4, v3
	s_and_saveexec_b64 s[4:5], vcc
	s_xor_b64 s[4:5], exec, s[4:5]
	s_cbranch_execz .LBB0_931
	v_readlane_b32 s6, v254, 15
	v_readlane_b32 s7, v254, 16
	s_waitcnt lgkmcnt(0)
	s_nop 3
	global_load_dword v2, v1, s[6:7] sc1
	s_waitcnt vmcnt(0)
	v_cmp_eq_u32_e32 vcc, v2, v0
	s_and_saveexec_b64 s[6:7], vcc
	s_cbranch_execz .LBB0_930
	s_mov_b32 s16, 1
	s_mov_b64 s[8:9], 0
	s_branch .LBB0_921
